# GMA->GMB grid barrier removed (same-lane dependency only); odd workgroups run rprep2 before attn2 and the gate GEMM before the late weight conversion
# speedup vs baseline: 1.0490x; 1.0047x over previous
; #define LAS __attribute__((address_space(3)))
; __device__ __forceinline__ void ph_attn2(Ctx& C) {
;     const int lane = lane_now(), wave = C.wave, tid = wave * 64 + lane, r31 = lane & 31, hh = lane >> 5;
;     const bf16* z = (const bf16*)(C.ws + WS_ZQKV); bf16* og = (bf16*)(C.ws + WS_OG); float* lse_o = (float*)(C.ws + WS_LSE);
;     LAS bf16* vt = (LAS bf16*)C.lds; LAS bf16* kim = (LAS bf16*)(C.lds + 64 * AT_VTS * 2);
;     for (int unit = C.bid; unit < 1536; unit += C.nb) {
;         const int g = unit >> 9, rem = unit & 511, h = rem & 7, tile64 = rem >> 3;
;         const int dsh = 2 * g, d = 1 << dsh, n = S >> dsh, res = tile64 & (d - 1), tl = tile64 >> dsh;
;         const int kbase = tl * 256 - 64, colq = g * 512 + h * 64, colk = 1536 + colq, colv = 3072 + colq;
;         const float slope_d = exp2f(-8.0f * (float)(g * 8 + h + 1) / 24.0f) * (float)d;
; #pragma unroll
;         for (int i = 0; i < 6; ++i) { const int kc = (tid >> 3) + 64 * i, ch = tid & 7, ki = kbase + kc; u32x4 w = (u32x4){0u, 0u, 0u, 0u}, wk = (u32x4){0u, 0u, 0u, 0u};
;             if (ki >= 0 && ki < n) { const bf16* rp = z + (size_t)((ki << dsh) + res) * NQKV + 8 * ch; w = *(const u32x4*)(rp + colv); wk = *(const u32x4*)(rp + colk); }
;             *(LAS u32x4*)(kim + kc * 72 + 8 * ch) = wk;
;             LAS bf16* dp = vt + (8 * ch) * AT_VTS + kc;
;             dp[0] = (bf16)(w.x & 0xffff); dp[AT_VTS] = (bf16)(w.x >> 16); dp[2 * AT_VTS] = (bf16)(w.y & 0xffff); dp[3 * AT_VTS] = (bf16)(w.y >> 16);
;             dp[4 * AT_VTS] = (bf16)(w.z & 0xffff); dp[5 * AT_VTS] = (bf16)(w.z >> 16); dp[6 * AT_VTS] = (bf16)(w.w & 0xffff); dp[7 * AT_VTS] = (bf16)(w.w >> 16); }
;         __syncthreads();
;         const int qb = tl * 256 + 32 * wave; const int qtok = ((qb + r31) << dsh) + res;
;         bf16x8 qf[4];
; #pragma unroll
;         for (int ks = 0; ks < 4; ++ks) qf[ks] = *(const bf16x8*)(z + (size_t)qtok * NQKV + colq + 16 * ks + 8 * hh);
;         f32x16 sacc[5];
; #pragma unroll
;         for (int kt = 0; kt < 5; ++kt) {
; #pragma unroll
;             for (int e = 0; e < 16; ++e) sacc[kt][e] = 0.f;
;             const LAS bf16* kp = kim + (32 * wave + 32 * kt + r31) * 72 + 8 * hh;
; #pragma unroll
;             for (int ks = 0; ks < 4; ++ks) { const bf16x8 kf = *(const LAS bf16x8*)(kp + 16 * ks); sacc[kt] = __builtin_amdgcn_mfma_f32_32x32x16_bf16(kf, qf[ks], sacc[kt], 0, 0, 0); } }
.LBB0_305:
	s_mov_b32 s100, 0
	s_load_dword s0, s[88:89], 0xd8
	s_waitcnt lgkmcnt(0)
	s_cmp_gt_i32 s0, 3
	s_cbranch_scc1 .LBB0_626
	s_load_dword s0, s[88:89], 0xdc
	s_waitcnt lgkmcnt(0)
	s_cmp_lt_i32 s0, 4
	s_cbranch_scc1 .LBB0_626
.Latt_setup:
	s_nop 0
	v_writelane_b32 v231, s88, 3
	s_load_dwordx2 s[78:79], s[88:89], 0xd0
	s_nop 0
	v_writelane_b32 v231, s89, 4
	s_nop 0
	v_readlane_b32 s0, v231, 1
	v_readlane_b32 s1, v231, 2
	s_load_dword s0, s[0:1], 0xe0
	v_readlane_b32 s1, v231, 0
	s_cmpk_gt_i32 s1, 0x5ff
	v_mbcnt_lo_u32_b32 v0, -1, 0
	v_mbcnt_hi_u32_b32 v0, -1, v0
	s_cmp_lg_u32 s100, 0
	s_cbranch_scc1 .Latt_go
	s_bitcmp1_b32 s1, 0
	s_cbranch_scc0 .Latt_go
	s_mov_b32 s100, 1
	s_branch .LBB0_326
.Latt_go:
	s_cmpk_gt_i32 s1, 0x5ff
	s_cbranch_scc1 .LBB0_326
	s_waitcnt lgkmcnt(0)
	s_add_u32 s80, s78, 0x3a00000
	s_addc_u32 s81, s79, 0
	s_add_u32 s82, s78, 0x1ba00000
	s_addc_u32 s83, s79, 0
	s_add_u32 s84, s78, 0x1ea00000
	s_addc_u32 s85, s79, 0
	s_lshl_b32 s1, s92, 6
	v_ashrrev_i32_e32 v1, 5, v0
	v_add_u32_e32 v2, s1, v0
	v_and_b32_e32 v3, 7, v0
	v_and_b32_e32 v186, 31, v0
	v_ashrrev_i32_e32 v187, 3, v2
	v_lshlrev_b32_e32 v2, 4, v3
	v_lshlrev_b32_e32 v84, 2, v1
	v_add_u32_e32 v188, 0, v2
	v_mul_u32_u24_e32 v4, 0x1830, v3
	v_mov_b32_e32 v3, 0
	s_lshl_b32 s94, s92, 5
	v_lshlrev_b32_e32 v82, 3, v1
	v_lshl_add_u32 v42, v1, 4, 0
	v_sub_u32_e32 v1, v84, v186
	s_add_i32 s1, s1, 0
	v_cmp_gt_u32_e64 s[2:3], 32, v0
	v_lshlrev_b32_e32 v0, 1, v187
	v_lshl_add_u64 v[80:81], s[80:81], 0, v[2:3]
	v_subrev_u32_e32 v2, 64, v1
	v_add_u32_e32 v43, s1, v82
	s_movk_i32 s1, 0x90
	v_add3_u32 v191, v188, v4, v0
	v_or_b32_e32 v0, s94, v186
	s_add_i32 s4, s94, 32
	v_cvt_f32_i32_e32 v86, v2
	v_mul_lo_u32 v48, v0, s1
	v_or_b32_e32 v0, s4, v186
	s_add_i32 s4, s94, 64
	v_mul_lo_u32 v49, v0, s1
	v_or_b32_e32 v0, s4, v186
	s_add_i32 s4, s94, 0x60
	v_mul_lo_u32 v50, v0, s1
	v_or_b32_e32 v0, s4, v186
	s_add_i32 s4, s94, 0x80
	v_mul_lo_u32 v51, v0, s1
	v_or_b32_e32 v0, s4, v186
	v_mul_lo_u32 v190, v187, s1
	v_mul_lo_u32 v52, v0, s1
	s_mov_b32 s1, 0xc2800000
	v_add_f32_e32 v0, 2.0, v86
	s_mov_b32 s38, 0x42000000
	v_add_f32_e32 v87, 1.0, v86
	v_and_b32_e32 v89, 0x7fffffff, v0
	v_cmp_le_f32_e64 s[8:9], s1, v0
	v_add_f32_e32 v0, 0x41d80000, v86
	s_mov_b32 s39, 0x42040000
	v_cmp_lt_i32_e64 s[4:5], -1, v1
	v_and_b32_e32 v103, 0x7fffffff, v0
	v_cmp_le_f32_e64 s[36:37], s1, v0
	v_pk_add_f32 v[0:1], v[86:87], s[38:39] op_sel_hi:[0,1]
	s_mov_b32 s38, 0x420c0000
	v_add_f32_e32 v2, 0x42080000, v86
	s_mov_b32 s39, 0x42200000
	v_and_b32_e32 v105, 0x7fffffff, v2
	v_pk_add_f32 v[2:3], v[86:87], s[38:39] op_sel_hi:[0,1]
	s_mov_b32 s38, 0x42240000
	s_mov_b32 s39, 0x42280000
	v_pk_add_f32 v[4:5], v[86:87], s[38:39] op_sel_hi:[0,1]
	s_mov_b32 s38, 0x422c0000
	s_mov_b32 s39, 0x42400000
	v_pk_add_f32 v[6:7], v[86:87], s[38:39] op_sel_hi:[0,1]
	s_mov_b32 s38, 0x42440000
	s_mov_b32 s39, 0x42480000
	v_pk_add_f32 v[8:9], v[86:87], s[38:39] op_sel_hi:[0,1]
	s_mov_b32 s38, 0x424c0000
	s_mov_b32 s39, 0x42600000
	v_pk_add_f32 v[10:11], v[86:87], s[38:39] op_sel_hi:[0,1]
	s_mov_b32 s38, 0x42640000
	s_mov_b32 s39, 0x42680000
	v_pk_add_f32 v[12:13], v[86:87], s[38:39] op_sel_hi:[0,1]
	s_mov_b32 s38, 0x42860000
	v_add_f32_e32 v16, 0x42840000, v86
	s_mov_b32 s39, 0x42900000
	v_and_b32_e32 v109, 0x7fffffff, v16
	v_pk_add_f32 v[16:17], v[86:87], s[38:39] op_sel_hi:[0,1]
	s_mov_b32 s38, 0x42920000
	s_mov_b32 s39, 0x42940000
	v_pk_add_f32 v[18:19], v[86:87], s[38:39] op_sel_hi:[0,1]
	s_mov_b32 s38, 0x42960000
	s_mov_b32 s39, 0x42a00000
	v_pk_add_f32 v[20:21], v[86:87], s[38:39] op_sel_hi:[0,1]
	s_mov_b32 s38, 0x42a20000
	s_mov_b32 s39, 0x42a40000
	v_pk_add_f32 v[22:23], v[86:87], s[38:39] op_sel_hi:[0,1]
	s_mov_b32 s38, 0x42a60000
	s_mov_b32 s39, 0x42b00000
	v_pk_add_f32 v[24:25], v[86:87], s[38:39] op_sel_hi:[0,1]
	s_mov_b32 s38, 0x42b20000
	s_mov_b32 s39, 0x42b40000
	v_pk_add_f32 v[26:27], v[86:87], s[38:39] op_sel_hi:[0,1]
	s_mov_b32 s38, 0x42c00000
	v_add_f32_e32 v28, 0x42b60000, v86
	s_mov_b32 s39, 0x42c20000
	v_and_b32_e32 v111, 0x7fffffff, v28
	v_pk_add_f32 v[28:29], v[86:87], s[38:39] op_sel_hi:[0,1]
	s_mov_b32 s38, 0x42c60000
	v_add_f32_e32 v30, 0x42c40000, v86
	s_mov_b32 s39, 0x42d00000
	v_and_b32_e32 v113, 0x7fffffff, v30
	v_pk_add_f32 v[30:31], v[86:87], s[38:39] op_sel_hi:[0,1]
	s_mov_b32 s38, 0x42d20000
	s_mov_b32 s39, 0x42d40000
	v_pk_add_f32 v[32:33], v[86:87], s[38:39] op_sel_hi:[0,1]
	s_mov_b32 s38, 0x42d60000
	s_mov_b32 s39, 0x42e00000
	v_pk_add_f32 v[34:35], v[86:87], s[38:39] op_sel_hi:[0,1]
	s_mov_b32 s38, 0x42e20000
	s_mov_b32 s39, 0x42e40000
	v_pk_add_f32 v[36:37], v[86:87], s[38:39] op_sel_hi:[0,1]
	s_mov_b32 s38, 0x42e60000
	s_mov_b32 s39, 0x42f00000
	v_pk_add_f32 v[38:39], v[86:87], s[38:39] op_sel_hi:[0,1]
	s_mov_b32 s38, 0x42f20000
	s_mov_b32 s39, 0x42f40000
	s_mov_b32 s10, 0x40400000
	s_mov_b32 s14, 0x41100000
	s_mov_b32 s18, 0x41300000
	s_mov_b32 s22, 0x41880000
	s_mov_b32 s88, 0x41980000
	s_mov_b32 s30, 0x41c80000
	s_mov_b32 s68, 0x42800000
	v_pk_add_f32 v[40:41], v[86:87], s[38:39] op_sel_hi:[0,1]
	v_add_f32_e32 v53, 0x42f60000, v86
	s_mov_b32 s38, 0x43000000
	s_mov_b32 s44, 0x43030000
	s_mov_b32 s48, 0x43090000
	s_mov_b32 s52, 0x430b0000
; __device__ __forceinline__ void ph_attn2(Ctx& C) {
;     ...
;         const float LOG2E = 1.44269504f, slope2 = slope_d * LOG2E, c0f = (float)(4 * hh - 64 - r31);
;         const bool edge = (tl == 0) || (tl == (n >> 8) - 1);
;         float m = -3.0e38f;
; #pragma unroll
;         for (int kt = 0; kt < 5; ++kt)
; #pragma unroll
;             for (int e = 0; e < 16; ++e) { const float relf = (float)(32 * kt + (e & 3) + 8 * (e >> 2)) + c0f; float sc = sacc[kt][e] * LOG2E - slope2 * __builtin_fabsf(relf);
;                 if (kt == 0) sc = relf >= -64.0f ? sc : -1e30f;
;                 if (kt == 4) sc = relf <= 64.0f ? sc : -1e30f;
;                 sacc[kt][e] = sc; }
	s_mov_b32 s56, 0x43110000
	s_mov_b32 s60, 0x43130000
	s_mov_b32 s64, 0x43190000
	s_mov_b32 s11, 0x41000000
	s_mov_b32 s15, 0x41200000
	s_mov_b32 s19, 0x41800000
	s_mov_b32 s23, 0x41900000
	s_mov_b32 s89, 0x41c00000
	s_mov_b32 s31, 0x41d00000
	v_add_f32_e32 v14, 0x426c0000, v86
	s_mov_b32 s69, 0x42820000
	v_and_b32_e32 v115, 0x7fffffff, v53
	s_mov_b32 s39, 0x43010000
	v_add_f32_e32 v53, 0x43020000, v86
	s_mov_b32 s45, 0x43080000
	s_mov_b32 s49, 0x430a0000
	s_mov_b32 s53, 0x43100000
	s_mov_b32 s57, 0x43120000
	s_mov_b32 s61, 0x43180000
	s_mov_b32 s65, 0x431a0000
	v_add_u32_e32 v44, 0x2400, v190
	v_add_u32_e32 v45, 0x4800, v190
	v_add_u32_e32 v46, 0x6c00, v190
	v_add_u32_e32 v47, 0x9000, v190
	v_pk_add_f32 v[90:91], v[86:87], s[10:11] op_sel_hi:[0,1]
	v_pk_add_f32 v[92:93], v[86:87], s[14:15] op_sel_hi:[0,1]
	v_pk_add_f32 v[94:95], v[86:87], s[18:19] op_sel_hi:[0,1]
	v_pk_add_f32 v[96:97], v[86:87], s[22:23] op_sel_hi:[0,1]
	v_pk_add_f32 v[98:99], v[86:87], s[88:89] op_sel_hi:[0,1]
	v_pk_add_f32 v[100:101], v[86:87], s[30:31] op_sel_hi:[0,1]
	v_and_b32_e32 v107, 0x7fffffff, v14
	v_pk_add_f32 v[14:15], v[86:87], s[68:69] op_sel_hi:[0,1]
	v_pk_add_f32 v[116:117], v[86:87], s[38:39] op_sel_hi:[0,1]
	v_and_b32_e32 v119, 0x7fffffff, v53
	v_cmp_ge_f32_e64 s[42:43], s68, v53
	v_pk_add_f32 v[120:121], v[86:87], s[44:45] op_sel_hi:[0,1]
	v_pk_add_f32 v[122:123], v[86:87], s[48:49] op_sel_hi:[0,1]
	v_pk_add_f32 v[124:125], v[86:87], s[52:53] op_sel_hi:[0,1]
	v_pk_add_f32 v[126:127], v[86:87], s[56:57] op_sel_hi:[0,1]
	v_pk_add_f32 v[128:129], v[86:87], s[60:61] op_sel_hi:[0,1]
	v_pk_add_f32 v[130:131], v[86:87], s[64:65] op_sel_hi:[0,1]
	v_add_f32_e32 v192, 0x431b0000, v86
	v_mul_u32_u24_e32 v53, 0x308, v186
	v_mov_b32_e32 v114, 0x3fb8aa3b
	s_mov_b32 s87, 0
	v_ashrrev_i32_e32 v83, 31, v82
	v_subrev_u32_e32 v189, 64, v84
	v_ashrrev_i32_e32 v85, 31, v84
	s_movk_i32 s95, 0x2400
	v_cmp_le_f32_e64 s[6:7], s1, v87
	v_cmp_le_f32_e64 s[10:11], s1, v91
	v_cmp_le_f32_e64 s[12:13], s1, v90
	v_cmp_le_f32_e64 s[14:15], s1, v93
	v_cmp_le_f32_e64 s[16:17], s1, v92
	v_cmp_le_f32_e64 s[18:19], s1, v95
	v_cmp_le_f32_e64 s[20:21], s1, v94
	v_cmp_le_f32_e64 s[22:23], s1, v97
	v_cmp_le_f32_e64 s[24:25], s1, v96
	v_cmp_le_f32_e64 s[26:27], s1, v99
	v_cmp_le_f32_e64 s[28:29], s1, v98
	v_cmp_le_f32_e64 s[30:31], s1, v101
	v_cmp_le_f32_e64 s[34:35], s1, v100
	v_cmp_ge_f32_e64 s[38:39], s68, v117
	v_cmp_ge_f32_e64 s[40:41], s68, v116
	v_cmp_ge_f32_e64 s[44:45], s68, v121
	v_cmp_ge_f32_e64 s[46:47], s68, v120
	v_cmp_ge_f32_e64 s[48:49], s68, v123
	v_cmp_ge_f32_e64 s[50:51], s68, v122
	v_cmp_ge_f32_e64 s[52:53], s68, v125
	v_cmp_ge_f32_e64 s[54:55], s68, v124
	v_cmp_ge_f32_e64 s[56:57], s68, v127
	v_cmp_ge_f32_e64 s[58:59], s68, v126
	v_cmp_ge_f32_e64 s[60:61], s68, v129
	v_cmp_ge_f32_e64 s[62:63], s68, v128
	v_cmp_ge_f32_e64 s[64:65], s68, v131
	v_cmp_ge_f32_e64 s[66:67], s68, v130
	v_cmp_ge_f32_e64 s[68:69], s68, v192
	s_mov_b32 s88, 0x3fb8aa3b
	v_mov_b32_e32 v110, v114
	v_mov_b32_e32 v106, v114
	v_mov_b32_e32 v102, v114
	v_mov_b32_e32 v118, v114
	v_mov_b32_e32 v112, v114
	v_mov_b32_e32 v108, v114
	v_mov_b32_e32 v104, v114
	v_mov_b32_e32 v88, v114
	v_subrev_u32_e32 v193, 64, v187
	v_add_u32_e32 v194, v188, v44
	v_add_u32_e32 v195, v188, v45
	v_add_u32_e32 v196, v188, v46
	v_add_u32_e32 v197, v42, v48
	v_add_u32_e32 v198, v42, v49
	v_add_u32_e32 v199, v42, v50
	v_add_u32_e32 v200, v42, v51
	v_add_u32_e32 v201, v42, v52
	v_and_b32_e32 v132, 0x7fffffff, v86
	v_and_b32_e32 v135, 0x7fffffff, v1
	v_and_b32_e32 v134, 0x7fffffff, v0
	v_and_b32_e32 v137, 0x7fffffff, v3
	v_and_b32_e32 v136, 0x7fffffff, v2
	v_and_b32_e32 v139, 0x7fffffff, v5
	v_and_b32_e32 v138, 0x7fffffff, v4
	v_and_b32_e32 v141, 0x7fffffff, v7
	v_and_b32_e32 v140, 0x7fffffff, v6
	v_and_b32_e32 v143, 0x7fffffff, v9
	v_and_b32_e32 v142, 0x7fffffff, v8
	v_and_b32_e32 v145, 0x7fffffff, v11
	v_and_b32_e32 v144, 0x7fffffff, v10
	v_and_b32_e32 v147, 0x7fffffff, v13
	v_and_b32_e32 v146, 0x7fffffff, v12
	v_and_b32_e32 v149, 0x7fffffff, v15
	v_and_b32_e32 v148, 0x7fffffff, v14
	v_and_b32_e32 v151, 0x7fffffff, v17
	v_and_b32_e32 v150, 0x7fffffff, v16
	v_and_b32_e32 v153, 0x7fffffff, v19
	v_and_b32_e32 v152, 0x7fffffff, v18
	v_and_b32_e32 v155, 0x7fffffff, v21
	v_and_b32_e32 v154, 0x7fffffff, v20
	v_and_b32_e32 v157, 0x7fffffff, v23
	v_and_b32_e32 v156, 0x7fffffff, v22
	v_and_b32_e32 v159, 0x7fffffff, v25
	v_and_b32_e32 v158, 0x7fffffff, v24
	v_and_b32_e32 v161, 0x7fffffff, v27
	v_and_b32_e32 v160, 0x7fffffff, v26
	v_and_b32_e32 v163, 0x7fffffff, v29
	v_and_b32_e32 v162, 0x7fffffff, v28
	v_and_b32_e32 v165, 0x7fffffff, v31
	v_and_b32_e32 v164, 0x7fffffff, v30
	v_and_b32_e32 v167, 0x7fffffff, v33
	v_and_b32_e32 v166, 0x7fffffff, v32
	v_and_b32_e32 v169, 0x7fffffff, v35
	v_and_b32_e32 v168, 0x7fffffff, v34
	v_and_b32_e32 v171, 0x7fffffff, v37
	v_and_b32_e32 v170, 0x7fffffff, v36
	v_and_b32_e32 v173, 0x7fffffff, v39
	v_and_b32_e32 v172, 0x7fffffff, v38
	v_and_b32_e32 v175, 0x7fffffff, v41
	v_and_b32_e32 v174, 0x7fffffff, v40
	v_add_u32_e32 v86, v43, v53
	v_add_u32_e32 v202, v188, v47
	v_mov_b32_e32 v203, 0x42800000
	v_mov_b32_e32 v204, 0xf149f2ca
	v_readlane_b32 s96, v231, 0
	s_branch .LBB0_310

; #define PH(k, ...) do { if (ka->ph_lo <= (k) && (k) < ka->ph_hi) { MKCTX(); __VA_ARGS__; if ((k) == PROBE_DUP) { GSYNC(); __VA_ARGS__; } if ((k) + 1 < ka->ph_hi) GSYNC(); } } while (0)
; template <bool COOP>
; __global__ void __launch_bounds__(NTHR, 2) mega(Args args) {
;     ...
;     PH(P_ATTPREP, ph_attn2(C); ph_rprep2(C));
.Latt_done:
	s_cmp_eq_u32 s100, 2
	s_cbranch_scc0 .LBB0_326
	v_readlane_b32 s88, v231, 3
	v_readlane_b32 s89, v231, 4
	s_nop 7
	s_branch .LBB0_570

; #define PH(k, ...) do { if (ka->ph_lo <= (k) && (k) < ka->ph_hi) { MKCTX(); __VA_ARGS__; if ((k) == PROBE_DUP) { GSYNC(); __VA_ARGS__; } if ((k) + 1 < ka->ph_hi) GSYNC(); } } while (0)
; template <bool COOP>
; __global__ void __launch_bounds__(NTHR, 2) mega(Args args) {
;     ...
;     PH(P_ATTPREP, ph_attn2(C); ph_rprep2(C));
.Lrp_done:
	s_cmp_eq_u32 s100, 1
	s_cbranch_scc0 .LBB0_570
	s_mov_b32 s100, 2
	s_branch .Latt_setup

; #define LAS __attribute__((address_space(3)))
; __device__ __forceinline__ int lane_now() { int l; asm volatile("v_mbcnt_lo_u32_b32 %0, -1, 0\n\tv_mbcnt_hi_u32_b32 %0, -1, %0" : "=v"(l)); return l; }
; template <class Mk> __device__ __forceinline__ void conv_run(Ctx& C, int nitems, const Mk& mk, LAS float* scr) {
;     const int lane = lane_now(); int it = C.gw; if (it >= nitems) return;
;     TrItem cur = mk(it); f32x4 v[8]; tr_load(cur, v, lane);
;     for (;;) { const int nit = it + C.ngw; const bool more = nit < nitems; TrItem nxt = cur; f32x4 w[8];
;         if (more) { nxt = mk(nit); tr_load(nxt, w, lane); }
;         tr_store(cur, v, scr, lane);
;         if (!more) break;
;         cur = nxt; it = nit;
; #pragma unroll
;         for (int i = 0; i < 8; ++i) v[i] = w[i]; }
; }
; __device__ __forceinline__ void conv_natural(Ctx& C, const float* W, int K, int N, bf16* Wt, LAS float* scr) {
;     const int nkb = K / 64;
;     conv_run(C, (N / 32) * nkb, [=](int it) { const int j32 = it / nkb, kb = it % nkb; return TrItem{W + (size_t)(kb * 64) * N + j32 * 32, N, 64, Wt + (size_t)(j32 * 32) * K + kb * 64, K}; }, scr);
; __device__ __forceinline__ void ph_g1b(Ctx& C) {
;     LAS float* scr = (LAS float*)(C.lds + C.wave * 16384);
;     conv_natural(C, C.ka->in[20], D, D, (bf16*)(C.ws + WS_WOUT), scr);
;     conv_wgu(C, scr);
;     conv_natural(C, C.ka->in[24], FF, D, (bf16*)(C.ws + WS_WD), scr);
;     __syncthreads();
.LBB0_953:
	s_mov_b32 s101, 0
	s_load_dword s0, s[88:89], 0xd8
	s_waitcnt lgkmcnt(0)
	s_cmp_gt_i32 s0, 9
	s_cbranch_scc1 .LBB0_1163
	s_load_dword s0, s[88:89], 0xdc
	s_waitcnt lgkmcnt(0)
	s_cmp_lt_i32 s0, 10
	s_cbranch_scc1 .LBB0_1163
.Lg1b_setup:
	v_readlane_b32 s0, v231, 1
	v_readlane_b32 s1, v231, 2
	s_load_dword s52, s[0:1], 0xe0
	v_readlane_b32 s0, v231, 0
	s_load_dwordx4 s[20:23], s[88:89], 0xc8
	s_lshl_b32 s0, s0, 3
	s_add_i32 s51, s92, s0
	s_lshl_b32 s0, s92, 14
	s_waitcnt lgkmcnt(0)
	s_lshl_b32 s50, s52, 3
	s_add_i32 s53, s0, 0
	s_cmpk_gt_i32 s51, 0x7ff
	v_mbcnt_lo_u32_b32 v46, -1, 0
	v_mbcnt_hi_u32_b32 v46, -1, v46
	s_cmp_lg_u32 s101, 0
	s_cbranch_scc1 .Lg1b_go
	v_readlane_b32 s0, v231, 0
	s_nop 0
	s_bitcmp1_b32 s0, 0
	s_cbranch_scc0 .Lg1b_go
	s_mov_b32 s101, 1
	s_branch .LBB0_1086
.Lg1b_go:
	s_cmpk_gt_i32 s51, 0x7ff
	s_cbranch_scc1 .LBB0_994
	s_ashr_i32 s0, s51, 31
	s_lshr_b32 s0, s0, 27
	s_add_i32 s0, s51, s0
	s_load_dwordx2 s[2:3], s[88:89], 0xa0
	s_and_b32 s26, s0, 0xffffffe0
	s_sub_i32 s0, s51, s26
	s_lshl_b32 s24, s0, 6
	s_ashr_i32 s25, s24, 31
	s_lshl_b64 s[0:1], s[24:25], 13
	s_waitcnt lgkmcnt(0)
	s_add_u32 s4, s2, s0
	s_addc_u32 s5, s3, s1
	s_ashr_i32 s27, s26, 31
	s_lshl_b64 s[0:1], s[26:27], 2
	s_add_u32 s28, s4, s0
	s_addc_u32 s29, s5, s1
	v_ashrrev_i32_e32 v24, 3, v46
	v_lshlrev_b32_e32 v0, 2, v46
	s_cmp_lg_u64 s[2:3], 0
	v_and_b32_e32 v47, 28, v0
	s_cselect_b64 s[18:19], -1, 0
	v_cmp_gt_i32_e32 vcc, 64, v24
	v_mov_b32_e32 v0, 0
	s_and_b64 s[4:5], s[18:19], vcc
	v_ashrrev_i32_e32 v25, 31, v24
	v_lshlrev_b32_e32 v64, 2, v47
	v_mov_b32_e32 v4, 0
	v_mov_b32_e32 v5, 0
	v_mov_b32_e32 v6, 0
	v_mov_b32_e32 v7, 0
	s_and_saveexec_b64 s[6:7], s[4:5]
	s_cbranch_execz .LBB0_958
	v_lshlrev_b64 v[2:3], 13, v[24:25]
	v_lshl_add_u64 v[2:3], s[28:29], 0, v[2:3]
	v_mov_b32_e32 v65, 0
	v_lshl_add_u64 v[2:3], v[2:3], 0, v[64:65]
	global_load_dwordx4 v[4:7], v[2:3], off nt

; __device__ __forceinline__ int lane_now() { int l; asm volatile("v_mbcnt_lo_u32_b32 %0, -1, 0\n\tv_mbcnt_hi_u32_b32 %0, -1, %0" : "=v"(l)); return l; }
; #define PG8_LAS __attribute__((address_space(3)))
; template <class Epi, class Sched, bool ALIGN_EPI = false, bool SP2 = false>
; __device__ __forceinline__ void gemm_phase(PG8_LAS unsigned char* lds, const Gemm g, const Sched& S, const Epi& E, const int wid) {
;     const int lane = lane_now(), tid = wid * 64 + lane, wr = wid >> 2, wc = wid & 3, fr = lane & 15, fq = lane >> 4;
;     const int K = g.K, nt = K / BK;
;     unsigned voffA[2], voffB[2];
; #pragma unroll
;     for (int i = 0; i < 2; ++i) { int R, C; stage_rc(tid * 16 + i * 8192, R, C); const int Rb = Epi::PERM ? ((R & ~31) + perm32(R & 31)) : R;
;         voffA[i] = (unsigned)(R * K + C) * 2u; voffB[i] = (unsigned)(Rb * K + C) * 2u; }
;     const size_t kstep = (size_t)(BK * 2);
;     const size_t hstep = (size_t)HALF * K * 2;
;     const size_t tstep = 2 * hstep;
;     const unsigned ldsw = (unsigned)wid * 1024u;
;     const int aoff = lds_byte(wr * 64 + fr, fq * 8), boff = lds_byte(wc * 32 + fr, fq * 8);
;     ...
;     Unit cur, nxt; int ui = 0;
;     if (!S.next(0, cur)) return;
;     f32x4 acc[2][2][4][2];
; #pragma unroll
;     for (int a = 0; a < 2; ++a)
; #pragma unroll
;         for (int b = 0; b < 2; ++b)
; #pragma unroll
;             for (int m = 0; m < 4; ++m)
; #pragma unroll
;                 for (int n = 0; n < 2; ++n) acc[a][b][m][n] = (f32x4){0.f, 0.f, 0.f, 0.f};
;     bf16x8 At[4][2], B0[2][2], B1[2][2];
;     const char* cA = (const char*)g.A + (size_t)cur.pm * tstep; const char* cB = (const char*)g.Bt + (size_t)cur.pn * tstep;
;     S.a_ready(cur);
;     if constexpr (SP2) {
;         PG8_STAGE(PG8_SB(0, 0), cB, voffB); PG8_STAGE(PG8_SB(0, 1), cB + hstep, voffB); PG8_STAGE(PG8_SA(0, 0), cA, voffA); PG8_STAGE(PG8_SA(0, 1), cA + hstep, voffA);
;         if (wr == 1) PG8_BAR;
;         PG8_WAIT_V(2); PG8_BAR;
;         PG8_STAGE(PG8_SB(1, 0), cB + kstep, voffB); PG8_STAGE(PG8_SA(1, 0), cA + kstep, voffA); PG8_STAGE(PG8_SB(1, 1), cB + hstep + kstep, voffB);
;         PG8_WAIT_V(6); PG8_BAR;
; __device__ __forceinline__ void ph_g1b(Ctx& C) {
;     ...
;     __syncthreads();
;     ...
;     EpiG1B8 E{(bf16*)(C.ws + WS_ZG), C.ka->in[3]};
;     gemm8(C, (const bf16*)(C.dout + DO_H1), (const bf16*)(C.ws + WS_WIN) + (size_t)N1A * D, NGATE, D, E);
.LBB0_1086:
	s_cmp_eq_u32 s101, 2
	s_cbranch_scc1 .LBB0_1107
	s_movk_i32 s0, 0x1000
	s_movk_i32 s4, 0x800
	s_waitcnt vmcnt(0)
	s_barrier
	s_ashr_i32 s1, s0, 31
	s_lshr_b32 s1, s1, 24
	s_add_i32 s0, s0, s1
	s_ashr_i32 s1, s0, 8
	s_lshl_b32 s2, s1, 6
	v_readlane_b32 s0, v231, 0
	s_cmp_ge_i32 s0, s2
	v_mbcnt_lo_u32_b32 v12, -1, 0
	v_mbcnt_hi_u32_b32 v12, -1, v12
	s_cbranch_scc1 .LBB0_1107
	s_add_u32 s53, s22, 0x2000000
	s_addc_u32 s54, s23, 0
	s_lshl_b32 s55, s92, 10
	v_lshlrev_b32_e32 v13, 4, v12
	v_add_u32_e32 v0, s55, v13
	v_add_u32_e32 v1, 0x2000, v0
	v_ashrrev_i32_e32 v2, 31, v1
	v_lshrrev_b32_e32 v2, 22, v2
	v_add_u32_e32 v2, v1, v2
	v_ashrrev_i32_e32 v2, 10, v2
	v_mul_i32_i24_e32 v3, 0x400, v2
	v_sub_u32_e32 v1, v1, v3
	v_lshrrev_b32_e32 v3, 4, v1
	v_bitop3_b32 v1, v3, v1, 32 bitop3:0x6c
	v_ashrrev_i32_e32 v3, 31, v1
	v_lshrrev_b32_e32 v3, 26, v3
	v_add_u32_e32 v3, v1, v3
	v_lshlrev_b32_e32 v5, 3, v2
	v_lshlrev_b32_e32 v2, 5, v2
	v_and_b32_e32 v14, 32, v2
	v_and_b32_e32 v2, 0xffc0, v3
	v_sub_u32_e32 v1, v1, v2
	v_ashrrev_i32_e32 v4, 6, v3
	v_and_b32_e32 v5, -16, v5
	v_lshrrev_b16_e32 v2, 7, v1
	v_add_u32_e32 v5, v4, v5
	v_and_b32_e32 v2, 1, v2
	v_and_b32_e32 v4, 3, v4
	s_mov_b32 s3, 0x7fffffe0
	v_lshrrev_b32_e32 v6, 2, v5
	v_lshlrev_b32_e32 v7, 1, v5
	v_add_u16_e32 v1, v1, v2
	v_mov_b32_e32 v2, 1
	v_and_or_b32 v4, v5, s3, v4
	v_and_b32_e32 v6, 4, v6
	v_and_b32_e32 v7, 24, v7
	v_ashrrev_i16_sdwa v1, v2, sext(v1) dst_sel:DWORD dst_unused:UNUSED_PAD src0_sel:DWORD src1_sel:BYTE_0
	v_or3_b32 v4, v4, v6, v7
	v_bfe_i32 v15, v1, 0, 16
	v_mul_lo_u32 v4, v4, s4
	v_add_u32_e32 v1, v14, v15
	v_mul_lo_u32 v16, v5, s4
	v_add_lshl_u32 v144, v4, v1, 1
	v_add_lshl_u32 v146, v1, v16, 1
	v_ashrrev_i32_e32 v1, 31, v0
	v_lshrrev_b32_e32 v1, 22, v1
	v_add_u32_e32 v1, v0, v1
	v_ashrrev_i32_e32 v1, 10, v1
	v_mul_i32_i24_e32 v3, 0x400, v1
	v_sub_u32_e32 v0, v0, v3
	v_lshrrev_b32_e32 v3, 4, v0
	v_bitop3_b32 v0, v3, v0, 32 bitop3:0x6c
	v_ashrrev_i32_e32 v3, 31, v0
	v_lshrrev_b32_e32 v3, 26, v3
	v_add_u32_e32 v3, v0, v3
	v_lshlrev_b32_e32 v5, 3, v1
	v_ashrrev_i32_e32 v4, 6, v3
	v_and_b32_e32 v5, -16, v5
	v_readlane_b32 s7, v231, 0
	v_add_u32_e32 v5, v4, v5
	v_and_b32_e32 v4, 3, v4
	s_ashr_i32 s57, s7, 31
	v_and_or_b32 v4, v5, s3, v4
	s_lshr_b32 s3, s57, 29
	s_add_i32 s3, s7, s3
	s_ashr_i32 s5, s4, 31
	s_lshl_b32 s56, s1, 3
	s_ashr_i32 s6, s3, 3
	s_and_b32 s3, s3, -8
	s_ashr_i32 s0, s92, 2
	s_lshl_b64 s[12:13], s[4:5], 8
	s_lshl_b64 s[14:15], s[4:5], 9
	s_sub_i32 s3, s7, s3
	s_or_b32 s58, s56, 1
	s_cmp_lt_i32 s3, 0
	v_lshlrev_b32_e32 v1, 5, v1
	s_cselect_b32 s7, s58, s56
	s_lshl_b32 s59, s1, 2
	v_and_b32_e32 v17, 32, v1
	v_and_b32_e32 v1, 0xc0, v3
	s_abs_i32 s60, s59
	v_sub_u32_e32 v0, v0, v1
	v_cvt_f32_u32_e32 v1, s60
	s_mul_i32 s3, s7, s3
	s_sub_i32 s7, 0, s60
	s_add_i32 s3, s3, s6
	v_rcp_iflag_f32_e32 v1, v1
	s_ashr_i32 s6, s3, 31
	s_bfe_i32 s61, s1, 0x1001d
	s_xor_b32 s1, s6, s61
	v_mul_f32_e32 v1, 0x4f7ffffe, v1
	v_cvt_u32_f32_e32 v1, v1
	s_abs_i32 s6, s3
	v_lshrrev_b32_e32 v6, 2, v5
	v_lshlrev_b32_e32 v7, 1, v5
	v_readfirstlane_b32 s62, v1
	s_mul_i32 s7, s7, s62
	s_mul_hi_u32 s7, s62, s7
	s_add_i32 s62, s62, s7
	s_mul_hi_u32 s7, s6, s62
	s_mul_i32 s8, s7, s60
	s_sub_i32 s6, s6, s8
	s_add_i32 s8, s7, 1
	s_sub_i32 s9, s6, s60
	s_cmp_ge_u32 s6, s60
	s_cselect_b32 s7, s8, s7
	s_cselect_b32 s6, s9, s6
	s_add_i32 s8, s7, 1
	s_cmp_ge_u32 s6, s60
	s_cselect_b32 s6, s8, s7
	s_xor_b32 s6, s6, s1
	s_sub_i32 s1, s6, s1
	s_lshl_b32 s6, s1, 2
	s_sub_i32 s7, 64, s6
	s_min_i32 s7, s7, 4
	s_abs_i32 s8, s7
	v_cvt_f32_u32_e32 v1, s8
	v_and_b32_e32 v6, 4, v6
	v_and_b32_e32 v7, 24, v7
	v_ashrrev_i16_sdwa v0, v2, sext(v0) dst_sel:DWORD dst_unused:UNUSED_PAD src0_sel:DWORD src1_sel:BYTE_0
	v_or3_b32 v4, v4, v6, v7
	v_bfe_i32 v18, v0, 0, 16
	v_mul_lo_u32 v4, v4, s4
	v_add_u32_e32 v0, v17, v18
	v_mul_lo_u32 v19, v5, s4
	v_add_lshl_u32 v148, v4, v0, 1
	v_add_lshl_u32 v150, v0, v19, 1
	v_rcp_iflag_f32_e32 v0, v1
	s_sub_i32 s10, 0, s8
	s_mul_i32 s1, s1, s59
	s_sub_i32 s1, s3, s1
	v_mul_f32_e32 v0, 0x4f7ffffe, v0
	v_cvt_u32_f32_e32 v0, v0
	s_abs_i32 s9, s1
	s_xor_b32 s3, s1, s7
	s_ashr_i32 s3, s3, 31
	v_readfirstlane_b32 s11, v0
	s_mul_i32 s10, s10, s11
	s_mul_hi_u32 s10, s11, s10
	s_add_i32 s11, s11, s10
	s_mul_hi_u32 s10, s9, s11
	s_mul_i32 s11, s10, s8
	s_sub_i32 s9, s9, s11
	s_add_i32 s11, s10, 1
	s_sub_i32 s16, s9, s8
	s_cmp_ge_u32 s9, s8
	s_cselect_b32 s10, s11, s10
	s_cselect_b32 s9, s16, s9
	s_add_i32 s11, s10, 1
	s_cmp_ge_u32 s9, s8
	s_cselect_b32 s8, s11, s10
	s_xor_b32 s8, s8, s3
	s_sub_i32 s11, s8, s3
	s_mul_i32 s3, s11, s7
	s_sub_i32 s1, s1, s3
	s_add_i32 s10, s1, s6
	s_lshr_b64 s[6:7], s[4:5], 23
	s_ashr_i32 s1, s10, 31
	s_ashr_i32 s7, s11, 31
	s_mul_i32 s1, s14, s1
	s_mul_hi_u32 s3, s14, s10
	s_mul_i32 s7, s14, s7
	s_mul_hi_u32 s8, s14, s11
	s_add_i32 s1, s3, s1
	s_mul_i32 s3, s6, s10
	s_add_i32 s7, s8, s7
	s_mul_i32 s6, s6, s11
	s_add_i32 s1, s1, s3
	s_add_i32 s7, s7, s6
	s_mul_i32 s6, s14, s11
	s_add_u32 s6, s53, s6
	s_addc_u32 s7, s54, s7
	s_add_i32 s63, s55, 0
	s_add_i32 m0, s63, 0x10000
	s_mul_i32 s3, s14, s10
	global_load_lds_dwordx4 v148, s[6:7]
	s_add_i32 m0, s63, 0x12000
	s_add_u32 s18, s6, s12
	global_load_lds_dwordx4 v144, s[6:7]
	s_addc_u32 s19, s7, s13
	s_add_i32 m0, s63, 0x14000
	v_mov_b32_e32 v149, 0
	global_load_lds_dwordx4 v148, s[18:19]
	s_add_i32 m0, s63, 0x16000
	s_add_u32 s8, s20, s3
	s_addc_u32 s9, s21, s1
	s_add_i32 s64, s63, 0x2000
	global_load_lds_dwordx4 v144, s[18:19]
	s_mov_b32 m0, s63
	s_add_u32 s16, s8, s12
	global_load_lds_dwordx4 v150, s[8:9]
	s_mov_b32 m0, s64
	s_addc_u32 s17, s9, s13
	s_add_i32 s65, s63, 0x4000
	global_load_lds_dwordx4 v146, s[8:9]
	s_mov_b32 m0, s65
	s_add_i32 s66, s63, 0x6000
	global_load_lds_dwordx4 v150, s[16:17]
	s_mov_b32 m0, s66
	v_mov_b32_e32 v145, v149
	global_load_lds_dwordx4 v146, s[16:17]
	s_load_dwordx2 s[16:17], s[88:89], 0x18
	v_mov_b32_e32 v151, v149
	v_mov_b32_e32 v147, v149
	s_cmp_eq_u32 s0, 1
	s_mov_b32 s67, 0
	v_lshl_add_u64 v[8:9], s[6:7], 0, v[148:149]
	v_lshl_add_u64 v[4:5], s[6:7], 0, v[144:145]
	v_lshl_add_u64 v[2:3], s[18:19], 0, v[148:149]
	v_lshl_add_u64 v[0:1], s[18:19], 0, v[144:145]
	v_lshl_add_u64 v[6:7], s[8:9], 0, v[150:151]
	s_cselect_b64 s[18:19], -1, 0
	s_cmp_lg_u32 s0, 1
	v_lshl_add_u64 v[10:11], s[8:9], 0, v[146:147]
	s_cbranch_scc1 .LBB0_1089
	s_barrier

; #define LAS __attribute__((address_space(3)))
; __device__ __forceinline__ void ph_g1b(Ctx& C) {
;     LAS float* scr = (LAS float*)(C.lds + C.wave * 16384);
;     conv_natural(C, C.ka->in[20], D, D, (bf16*)(C.ws + WS_WOUT), scr);
;     conv_wgu(C, scr);
;     conv_natural(C, C.ka->in[24], FF, D, (bf16*)(C.ws + WS_WD), scr);
;     __syncthreads();
;     ...
;     EpiG1B8 E{(bf16*)(C.ws + WS_ZG), C.ka->in[3]};
;     gemm8(C, (const bf16*)(C.dout + DO_H1), (const bf16*)(C.ws + WS_WIN) + (size_t)N1A * D, NGATE, D, E);
;     ...
;     EpiG1B E{(bf16*)(C.ws + WS_ZG), C.ka->in[3]};
;     gemm_simple(C, (const bf16*)(C.dout + DO_H1), (const bf16*)(C.ws + WS_WIN) + (size_t)N1A * D, NGATE, D, E);
;     ...
; }
.LBB0_1107:
	s_cmp_eq_u32 s101, 1
	s_cbranch_scc0 .Lg1b_fin
	s_mov_b32 s101, 2
	s_branch .Lg1b_setup

; #define PH(k, ...) do { if (ka->ph_lo <= (k) && (k) < ka->ph_hi) { MKCTX(); __VA_ARGS__; if ((k) == PROBE_DUP) { GSYNC(); __VA_ARGS__; } if ((k) + 1 < ka->ph_hi) GSYNC(); } } while (0)
; template <bool COOP>
; __global__ void __launch_bounds__(NTHR, 2) mega(Args args) {
;     ...
;     PH(P_GMA, { EpiMerge8<false> E{(bf16*)(C.ws + WS_MERGED), (const bf16*)(C.ws + WS_ZG)}; gemm8(C, (const bf16*)(C.ws + WS_OATT), (const bf16*)(C.ws + WS_WBA), D, 512, E); });
;     PH(P_GMB, { EpiMerge8<true> E{(bf16*)(C.ws + WS_MERGED), (const bf16*)(C.ws + WS_ZG)}; gemm8(C, (const bf16*)(C.ws + WS_ORWKV), (const bf16*)(C.ws + WS_WBR), D, RW, E); });
.LBB0_1186:
	s_load_dword s0, s[88:89], 0xdc
	s_waitcnt lgkmcnt(0)
	s_cmp_lt_i32 s0, 12
	s_branch .LBB0_1242
	s_getreg_b32 s0, hwreg(HW_REG_XCC_ID, 0, 4)
	s_cmp_lg_u32 s92, 0
	s_mov_b64 s[4:5], 0
	s_cbranch_scc1 .LBB0_1189
	v_mbcnt_lo_u32_b32 v0, -1, 0
	v_mbcnt_hi_u32_b32 v0, -1, v0
	s_nop 0
	v_cmp_eq_u32_e32 vcc, 0, v0
	s_and_b64 s[4:5], vcc, exec

	.amdhsa_kernel _Z4megaILb1EEv4Args
		.amdhsa_group_segment_fixed_size 0
		.amdhsa_private_segment_fixed_size 0
		.amdhsa_kernarg_size 480
		.amdhsa_user_sgpr_count 2
		.amdhsa_user_sgpr_dispatch_ptr 0
		.amdhsa_user_sgpr_queue_ptr 0
		.amdhsa_user_sgpr_kernarg_segment_ptr 1
		.amdhsa_user_sgpr_dispatch_id 0
		.amdhsa_user_sgpr_kernarg_preload_length 0
		.amdhsa_user_sgpr_kernarg_preload_offset 0
		.amdhsa_user_sgpr_private_segment_size 0
		.amdhsa_uses_dynamic_stack 0
		.amdhsa_enable_private_segment 0
		.amdhsa_system_sgpr_workgroup_id_x 1
		.amdhsa_system_sgpr_workgroup_id_y 0
		.amdhsa_system_sgpr_workgroup_id_z 0
		.amdhsa_system_sgpr_workgroup_info 0
		.amdhsa_system_vgpr_workitem_id 2
		.amdhsa_next_free_vgpr 256
		.amdhsa_next_free_sgpr 102
		.amdhsa_accum_offset 256
		.amdhsa_reserve_vcc 1
		.amdhsa_float_round_mode_32 0
		.amdhsa_float_round_mode_16_64 0
		.amdhsa_float_denorm_mode_32 3
		.amdhsa_float_denorm_mode_16_64 3
		.amdhsa_dx10_clamp 1
		.amdhsa_ieee_mode 1
		.amdhsa_fp16_overflow 0
		.amdhsa_tg_split 0
		.amdhsa_exception_fp_ieee_invalid_op 0
		.amdhsa_exception_fp_denorm_src 0
		.amdhsa_exception_fp_ieee_div_zero 0
		.amdhsa_exception_fp_ieee_overflow 0
		.amdhsa_exception_fp_ieee_underflow 0
		.amdhsa_exception_fp_ieee_inexact 0
		.amdhsa_exception_int_div_zero 0
	.end_amdhsa_kernel

amdhsa.kernels:
  - .agpr_count:     0
    .args:
      - .offset:         0
        .size:           224
        .value_kind:     by_value
      - .offset:         224
        .size:           4
        .value_kind:     hidden_block_count_x
      - .offset:         228
        .size:           4
        .value_kind:     hidden_block_count_y
      - .offset:         232
        .size:           4
        .value_kind:     hidden_block_count_z
      - .offset:         236
        .size:           2
        .value_kind:     hidden_group_size_x
      - .offset:         238
        .size:           2
        .value_kind:     hidden_group_size_y
      - .offset:         240
        .size:           2
        .value_kind:     hidden_group_size_z
      - .offset:         242
        .size:           2
        .value_kind:     hidden_remainder_x
      - .offset:         244
        .size:           2
        .value_kind:     hidden_remainder_y
      - .offset:         246
        .size:           2
        .value_kind:     hidden_remainder_z
      - .offset:         264
        .size:           8
        .value_kind:     hidden_global_offset_x
      - .offset:         272
        .size:           8
        .value_kind:     hidden_global_offset_y
      - .offset:         280
        .size:           8
        .value_kind:     hidden_global_offset_z
      - .offset:         288
        .size:           2
        .value_kind:     hidden_grid_dims
      - .offset:         312
        .size:           8
        .value_kind:     hidden_multigrid_sync_arg
      - .offset:         344
        .size:           4
        .value_kind:     hidden_dynamic_lds_size
    .group_segment_fixed_size: 0
    .kernarg_segment_align: 8
    .kernarg_segment_size: 480
    .language:       OpenCL C
    .language_version:
      - 2
      - 0
    .max_flat_workgroup_size: 512
    .name:           _Z4megaILb1EEv4Args
    .private_segment_fixed_size: 0
    .sgpr_count:     108
    .sgpr_spill_count: 9
    .symbol:         _Z4megaILb1EEv4Args.kd
    .uniform_work_group_size: 1
    .uses_dynamic_stack: false
    .vgpr_count:     256
    .vgpr_spill_count: 0
    .wavefront_size: 64
  - .agpr_count:     0
    .args:
      - .offset:         0
        .size:           224
        .value_kind:     by_value
      - .offset:         224
        .size:           4
        .value_kind:     hidden_block_count_x
      - .offset:         228
        .size:           4
        .value_kind:     hidden_block_count_y
      - .offset:         232
        .size:           4
        .value_kind:     hidden_block_count_z
      - .offset:         236
        .size:           2
        .value_kind:     hidden_group_size_x
      - .offset:         238
        .size:           2
        .value_kind:     hidden_group_size_y
      - .offset:         240
        .size:           2
        .value_kind:     hidden_group_size_z
      - .offset:         242
        .size:           2
        .value_kind:     hidden_remainder_x
      - .offset:         244
        .size:           2
        .value_kind:     hidden_remainder_y
      - .offset:         246
        .size:           2
        .value_kind:     hidden_remainder_z
      - .offset:         264
        .size:           8
        .value_kind:     hidden_global_offset_x
      - .offset:         272
        .size:           8
        .value_kind:     hidden_global_offset_y
      - .offset:         280
        .size:           8
        .value_kind:     hidden_global_offset_z
      - .offset:         288
        .size:           2
        .value_kind:     hidden_grid_dims
      - .offset:         344
        .size:           4
        .value_kind:     hidden_dynamic_lds_size
    .group_segment_fixed_size: 0
    .kernarg_segment_align: 8
    .kernarg_segment_size: 480
    .language:       OpenCL C
    .language_version:
      - 2
      - 0
    .max_flat_workgroup_size: 512
    .name:           _Z4megaILb0EEv4Args
    .private_segment_fixed_size: 0
    .sgpr_count:     106
    .sgpr_spill_count: 11
    .symbol:         _Z4megaILb0EEv4Args.kd
    .uniform_work_group_size: 1
    .uses_dynamic_stack: false
    .vgpr_count:     232
    .vgpr_spill_count: 0
    .wavefront_size: 64
